# layer-0 context-query attention units (NA and diff) moved from workgroups 0-7 to workgroups 96-103 / 104-111, which run no fourier stage, to shorten the attention phase critical path
# speedup vs baseline: 1.0570x; 1.0034x over previous
.LBB0_489:
	s_waitcnt lgkmcnt(0)
	v_add_f32_e32 v34, v179, v32
	v_div_scale_f32 v35, s[0:1], v34, v34, 1.0
	v_rcp_f32_e32 v36, v35
	v_readlane_b32 s0, v255, 14
	v_readlane_b32 s1, v255, 15
	s_add_i32 s16, s16, 0xa0
	v_fma_f32 v37, -v35, v36, 1.0
	v_fmac_f32_e32 v36, v37, v36
	v_div_scale_f32 v37, vcc, 1.0, v34, 1.0
	v_mul_f32_e32 v38, v37, v36
	v_fma_f32 v39, -v35, v38, v37
	v_fmac_f32_e32 v38, v39, v36
	v_fma_f32 v35, -v35, v38, v37
	v_div_fmas_f32 v35, v35, v36, v38
	v_div_fixup_f32 v34, v35, v34, 1.0
	v_lshl_add_u64 v[32:33], v[174:175], 1, s[0:1]
	v_lshlrev_b64 v[36:37], 11, v[176:177]
	v_pk_mul_f32 v[16:17], v[16:17], v[34:35] op_sel_hi:[1,0]
	v_pk_mul_f32 v[18:19], v[18:19], v[34:35] op_sel_hi:[1,0]
	v_pk_mul_f32 v[0:1], v[0:1], v[34:35] op_sel_hi:[1,0]
	v_pk_mul_f32 v[2:3], v[2:3], v[34:35] op_sel_hi:[1,0]
	v_lshl_add_u64 v[32:33], v[32:33], 0, v[36:37]
	v_cvt_pk_bf16_f32 v16, v16, v17
	v_cvt_pk_bf16_f32 v17, v18, v19
	v_cvt_pk_bf16_f32 v0, v0, v1
	v_cvt_pk_bf16_f32 v1, v2, v3
	global_store_dwordx2 v[32:33], v[16:17], off
	v_pk_mul_f32 v[16:17], v[20:21], v[34:35] op_sel_hi:[1,0]
	v_pk_mul_f32 v[18:19], v[22:23], v[34:35] op_sel_hi:[1,0]
	global_store_dwordx2 v[32:33], v[0:1], off offset:64
	v_pk_mul_f32 v[0:1], v[4:5], v[34:35] op_sel_hi:[1,0]
	v_pk_mul_f32 v[2:3], v[6:7], v[34:35] op_sel_hi:[1,0]
	v_cvt_pk_bf16_f32 v16, v16, v17
	v_cvt_pk_bf16_f32 v17, v18, v19
	v_cvt_pk_bf16_f32 v0, v0, v1
	v_cvt_pk_bf16_f32 v1, v2, v3
	global_store_dwordx2 v[32:33], v[16:17], off offset:16
	v_pk_mul_f32 v[16:17], v[24:25], v[34:35] op_sel_hi:[1,0]
	v_pk_mul_f32 v[18:19], v[26:27], v[34:35] op_sel_hi:[1,0]
	global_store_dwordx2 v[32:33], v[0:1], off offset:80
	v_pk_mul_f32 v[0:1], v[8:9], v[34:35] op_sel_hi:[1,0]
	v_pk_mul_f32 v[2:3], v[10:11], v[34:35] op_sel_hi:[1,0]
	v_cvt_pk_bf16_f32 v16, v16, v17
	v_cvt_pk_bf16_f32 v17, v18, v19
	v_cvt_pk_bf16_f32 v0, v0, v1
	v_cvt_pk_bf16_f32 v1, v2, v3
	global_store_dwordx2 v[32:33], v[16:17], off offset:32
	v_pk_mul_f32 v[16:17], v[28:29], v[34:35] op_sel_hi:[1,0]
	v_pk_mul_f32 v[18:19], v[30:31], v[34:35] op_sel_hi:[1,0]
	global_store_dwordx2 v[32:33], v[0:1], off offset:96
	v_pk_mul_f32 v[0:1], v[12:13], v[34:35] op_sel_hi:[1,0]
	v_pk_mul_f32 v[2:3], v[14:15], v[34:35] op_sel_hi:[1,0]
	v_readlane_b32 s0, v255, 9
	v_cvt_pk_bf16_f32 v16, v16, v17
	v_cvt_pk_bf16_f32 v17, v18, v19
	v_cvt_pk_bf16_f32 v0, v0, v1
	v_cvt_pk_bf16_f32 v1, v2, v3
	s_cmp_ge_i32 s16, s0
	global_store_dwordx2 v[32:33], v[16:17], off offset:48
	global_store_dwordx2 v[32:33], v[0:1], off offset:112
	s_cbranch_scc1 .LBB0_526
	s_cmpk_lt_i32 s16, 0x100
	s_cbranch_scc1 .LBB0_526

.LBB0_561:
	v_mbcnt_lo_u32_b32 v64, -1, 0
	v_mbcnt_hi_u32_b32 v64, -1, v64
	v_mbcnt_lo_u32_b32 v65, -1, 0
	v_mbcnt_hi_u32_b32 v65, -1, v65
	s_lshl_b32 s20, s8, 1
	v_lshlrev_b32_e32 v64, 2, v64
	v_xor_b32_e32 v64, 0x80, v64
	ds_bpermute_b32 v64, v64, v128
	v_lshlrev_b32_e32 v65, 2, v65
	v_xor_b32_e32 v65, 0x80, v65
	ds_bpermute_b32 v65, v65, v129
	s_mov_b32 s9, s21
	s_waitcnt lgkmcnt(0)
	v_add_f32_e32 v64, v128, v64
	v_div_scale_f32 v66, s[10:11], v64, v64, 1.0
	v_rcp_f32_e32 v67, v66
	v_add_f32_e32 v65, v129, v65
	v_writelane_b32 v252, s8, 43
	v_lshlrev_b32_e32 v160, 1, v182
	v_fma_f32 v68, -v66, v67, 1.0
	v_fmac_f32_e32 v67, v68, v67
	v_div_scale_f32 v68, vcc, 1.0, v64, 1.0
	v_mul_f32_e32 v69, v68, v67
	v_fma_f32 v70, -v66, v69, v68
	v_fmac_f32_e32 v69, v70, v67
	v_fma_f32 v66, -v66, v69, v68
	v_div_fmas_f32 v66, v66, v67, v69
	v_div_fixup_f32 v64, v66, v64, 1.0
	v_div_scale_f32 v66, s[10:11], v65, v65, v120
	v_rcp_f32_e32 v67, v66
	v_readlane_b32 s10, v255, 5
	v_readlane_b32 s11, v255, 6
	v_writelane_b32 v252, s9, 44
	v_fma_f32 v68, -v66, v67, 1.0
	v_fmac_f32_e32 v67, v68, v67
	v_div_scale_f32 v68, vcc, v120, v65, v120
	v_mul_f32_e32 v69, v68, v67
	v_fma_f32 v70, -v66, v69, v68
	v_fmac_f32_e32 v69, v70, v67
	v_fma_f32 v66, -v66, v69, v68
	v_div_fmas_f32 v66, v66, v67, v69
	v_div_fixup_f32 v66, v66, v65, v120
	v_pk_mul_f32 v[26:27], v[26:27], v[66:67] op_sel_hi:[1,0]
	s_mov_b64 s[8:9], s[0:1]
	v_pk_fma_f32 v[68:69], v[10:11], v[64:65], v[26:27] op_sel_hi:[1,0,1] neg_lo:[0,0,1] neg_hi:[0,0,1]
	v_pk_mul_f32 v[10:11], v[28:29], v[66:67] op_sel_hi:[1,0]
	v_pk_mul_f32 v[62:63], v[62:63], v[66:67] op_sel_hi:[1,0]
	v_pk_fma_f32 v[10:11], v[12:13], v[64:65], v[10:11] op_sel_hi:[1,0,1] neg_lo:[0,0,1] neg_hi:[0,0,1]
	v_pk_mul_f32 v[12:13], v[30:31], v[66:67] op_sel_hi:[1,0]
	v_pk_mul_f32 v[18:19], v[18:19], v[66:67] op_sel_hi:[1,0]
	v_pk_fma_f32 v[12:13], v[14:15], v[64:65], v[12:13] op_sel_hi:[1,0,1] neg_lo:[0,0,1] neg_hi:[0,0,1]
	v_mbcnt_lo_u32_b32 v14, -1, 0
	v_mbcnt_hi_u32_b32 v14, -1, v14
	v_pk_mul_f32 v[50:51], v[50:51], v[66:67] op_sel_hi:[1,0]
	v_lshlrev_b32_e32 v14, 2, v14
	v_xor_b32_e32 v65, 0x80, v14
	v_lshlrev_b64 v[14:15], 11, v[122:123]
	v_lshl_add_u64 v[14:15], s[10:11], 0, v[14:15]
	v_lshl_add_u64 v[14:15], v[14:15], 0, s[20:21]
	v_lshl_add_u64 v[14:15], v[14:15], 0, v[160:161]
	v_lshlrev_b32_e32 v160, 2, v182
	v_lshl_add_u64 v[26:27], s[8:9], 0, v[160:161]
	v_pk_fma_f32 v[62:63], v[46:47], v[64:65], v[62:63] op_sel_hi:[1,0,1] neg_lo:[0,0,1] neg_hi:[0,0,1]
	v_pk_mul_f32 v[46:47], v[60:61], v[66:67] op_sel_hi:[1,0]
	v_pk_fma_f32 v[92:93], v[2:3], v[64:65], v[18:19] op_sel_hi:[1,0,1] neg_lo:[0,0,1] neg_hi:[0,0,1]
	v_pk_mul_f32 v[2:3], v[16:17], v[66:67] op_sel_hi:[1,0]
	v_pk_fma_f32 v[60:61], v[44:45], v[64:65], v[46:47] op_sel_hi:[1,0,1] neg_lo:[0,0,1] neg_hi:[0,0,1]
	flat_load_dwordx4 v[44:47], v[26:27] offset:128
	v_pk_fma_f32 v[96:97], v[0:1], v[64:65], v[2:3] op_sel_hi:[1,0,1] neg_lo:[0,0,1] neg_hi:[0,0,1]
	flat_load_dwordx4 v[0:3], v[26:27] offset:160
	v_pk_mul_f32 v[16:17], v[22:23], v[66:67] op_sel_hi:[1,0]
	v_pk_fma_f32 v[50:51], v[34:35], v[64:65], v[50:51] op_sel_hi:[1,0,1] neg_lo:[0,0,1] neg_hi:[0,0,1]
	v_pk_fma_f32 v[6:7], v[6:7], v[64:65], v[16:17] op_sel_hi:[1,0,1] neg_lo:[0,0,1] neg_hi:[0,0,1]
	v_pk_mul_f32 v[16:17], v[20:21], v[66:67] op_sel_hi:[1,0]
	v_pk_mul_f32 v[34:35], v[48:49], v[66:67] op_sel_hi:[1,0]
	v_pk_fma_f32 v[20:21], v[4:5], v[64:65], v[16:17] op_sel_hi:[1,0,1] neg_lo:[0,0,1] neg_hi:[0,0,1]
	flat_load_dwordx4 v[16:19], v[26:27] offset:192
	v_pk_fma_f32 v[48:49], v[32:33], v[64:65], v[34:35] op_sel_hi:[1,0,1] neg_lo:[0,0,1] neg_hi:[0,0,1]
	v_pk_mul_f32 v[54:55], v[54:55], v[66:67] op_sel_hi:[1,0]
	v_pk_mul_f32 v[58:59], v[58:59], v[66:67] op_sel_hi:[1,0]
	v_pk_mul_f32 v[78:79], v[48:49], v[48:49]
	v_pk_fma_f32 v[54:55], v[38:39], v[64:65], v[54:55] op_sel_hi:[1,0,1] neg_lo:[0,0,1] neg_hi:[0,0,1]
	v_pk_mul_f32 v[38:39], v[52:53], v[66:67] op_sel_hi:[1,0]
	v_pk_fma_f32 v[58:59], v[42:43], v[64:65], v[58:59] op_sel_hi:[1,0,1] neg_lo:[0,0,1] neg_hi:[0,0,1]
	v_pk_mul_f32 v[42:43], v[56:57], v[66:67] op_sel_hi:[1,0]
	v_pk_mul_f32 v[24:25], v[24:25], v[66:67] op_sel_hi:[1,0]
	v_pk_mul_f32 v[76:77], v[50:51], v[50:51]
	v_pk_fma_f32 v[52:53], v[36:37], v[64:65], v[38:39] op_sel_hi:[1,0,1] neg_lo:[0,0,1] neg_hi:[0,0,1]
	v_pk_fma_f32 v[56:57], v[40:41], v[64:65], v[42:43] op_sel_hi:[1,0,1] neg_lo:[0,0,1] neg_hi:[0,0,1]
	v_pk_fma_f32 v[8:9], v[8:9], v[64:65], v[24:25] op_sel_hi:[1,0,1] neg_lo:[0,0,1] neg_hi:[0,0,1]
	v_add_f32_e32 v64, v78, v79
	v_add_f32_e32 v64, v76, v64
	v_pk_mul_f32 v[82:83], v[52:53], v[52:53]
	v_add_f32_e32 v64, v77, v64
	v_add_f32_e32 v64, v82, v64
	v_pk_mul_f32 v[80:81], v[54:55], v[54:55]
	v_add_f32_e32 v64, v83, v64
	v_add_f32_e32 v64, v80, v64
	v_pk_mul_f32 v[86:87], v[56:57], v[56:57]
	v_add_f32_e32 v64, v81, v64
	v_add_f32_e32 v64, v86, v64
	v_pk_mul_f32 v[84:85], v[58:59], v[58:59]
	v_add_f32_e32 v64, v87, v64
	v_add_f32_e32 v64, v84, v64
	v_pk_mul_f32 v[90:91], v[60:61], v[60:61]
	v_add_f32_e32 v64, v85, v64
	v_add_f32_e32 v64, v90, v64
	v_pk_mul_f32 v[88:89], v[62:63], v[62:63]
	v_add_f32_e32 v64, v91, v64
	v_add_f32_e32 v64, v88, v64
	v_pk_mul_f32 v[98:99], v[96:97], v[96:97]
	v_add_f32_e32 v64, v89, v64
	v_add_f32_e32 v64, v98, v64
	v_pk_mul_f32 v[94:95], v[92:93], v[92:93]
	v_add_f32_e32 v64, v99, v64
	v_add_f32_e32 v64, v94, v64
	v_pk_mul_f32 v[4:5], v[20:21], v[20:21]
	v_add_f32_e32 v64, v95, v64
	v_add_f32_e32 v4, v4, v64
	v_pk_mul_f32 v[22:23], v[6:7], v[6:7]
	v_add_f32_e32 v4, v5, v4
	v_add_f32_e32 v4, v22, v4
	v_pk_mul_f32 v[24:25], v[8:9], v[8:9]
	v_add_f32_e32 v4, v23, v4
	v_add_f32_e32 v4, v24, v4
	v_pk_mul_f32 v[70:71], v[68:69], v[68:69]
	v_add_f32_e32 v4, v25, v4
	v_add_f32_e32 v4, v70, v4
	v_pk_mul_f32 v[72:73], v[10:11], v[10:11]
	v_add_f32_e32 v4, v71, v4
	v_add_f32_e32 v4, v72, v4
	v_pk_mul_f32 v[74:75], v[12:13], v[12:13]
	v_add_f32_e32 v4, v73, v4
	v_add_f32_e32 v4, v74, v4
	v_add_f32_e32 v4, v75, v4
	ds_bpermute_b32 v5, v65, v4
	flat_load_dwordx4 v[28:31], v[26:27]
	flat_load_dwordx4 v[32:35], v[26:27] offset:32
	flat_load_dwordx4 v[36:39], v[26:27] offset:64
	flat_load_dwordx4 v[40:43], v[26:27] offset:96
	s_waitcnt lgkmcnt(0)
	v_add_f32_e32 v4, v4, v5
	v_fmamk_f32 v4, v4, 0x3c800000, v208
	v_rsq_f32_e32 v4, v4
	s_add_i32 s14, s14, 0x98
	v_readlane_b32 s8, v255, 9
	s_cmp_ge_i32 s14, s8
	v_mul_f32_e32 v4, v121, v4
	v_pk_mul_f32 v[20:21], v[20:21], v[4:5] op_sel_hi:[1,0]
	v_pk_mul_f32 v[6:7], v[6:7], v[4:5] op_sel_hi:[1,0]
	s_waitcnt vmcnt(0)
	v_pk_mul_f32 v[0:1], v[0:1], v[20:21]
	v_pk_mul_f32 v[2:3], v[2:3], v[6:7]
	v_cvt_pk_bf16_f32 v0, v0, v1
	v_cvt_pk_bf16_f32 v1, v2, v3
	global_store_dwordx2 v[14:15], v[0:1], off offset:1104
	v_pk_mul_f32 v[0:1], v[8:9], v[4:5] op_sel_hi:[1,0]
	v_pk_mul_f32 v[2:3], v[68:69], v[4:5] op_sel_hi:[1,0]
	v_pk_mul_f32 v[0:1], v[16:17], v[0:1]
	v_pk_mul_f32 v[2:3], v[18:19], v[2:3]
	v_cvt_pk_bf16_f32 v0, v0, v1
	v_cvt_pk_bf16_f32 v1, v2, v3
	global_store_dwordx2 v[14:15], v[0:1], off offset:1120
	flat_load_dwordx4 v[0:3], v[26:27] offset:224
	v_pk_mul_f32 v[22:23], v[48:49], v[4:5] op_sel_hi:[1,0]
	v_pk_mul_f32 v[24:25], v[50:51], v[4:5] op_sel_hi:[1,0]
	v_pk_mul_f32 v[6:7], v[10:11], v[4:5] op_sel_hi:[1,0]
	v_pk_mul_f32 v[22:23], v[28:29], v[22:23]
	v_pk_mul_f32 v[24:25], v[30:31], v[24:25]
	v_cvt_pk_bf16_f32 v22, v22, v23
	v_cvt_pk_bf16_f32 v23, v24, v25
	global_store_dwordx2 v[14:15], v[22:23], off offset:1024
	v_pk_mul_f32 v[22:23], v[52:53], v[4:5] op_sel_hi:[1,0]
	v_pk_mul_f32 v[24:25], v[54:55], v[4:5] op_sel_hi:[1,0]
	v_pk_mul_f32 v[22:23], v[32:33], v[22:23]
	v_pk_mul_f32 v[24:25], v[34:35], v[24:25]
	v_cvt_pk_bf16_f32 v22, v22, v23
	v_cvt_pk_bf16_f32 v23, v24, v25
	global_store_dwordx2 v[14:15], v[22:23], off offset:1040
	v_pk_mul_f32 v[22:23], v[56:57], v[4:5] op_sel_hi:[1,0]
	v_pk_mul_f32 v[24:25], v[58:59], v[4:5] op_sel_hi:[1,0]
	v_pk_mul_f32 v[22:23], v[36:37], v[22:23]
	v_pk_mul_f32 v[24:25], v[38:39], v[24:25]
	v_cvt_pk_bf16_f32 v22, v22, v23
	v_cvt_pk_bf16_f32 v23, v24, v25
	global_store_dwordx2 v[14:15], v[22:23], off offset:1056
	v_pk_mul_f32 v[22:23], v[60:61], v[4:5] op_sel_hi:[1,0]
	v_pk_mul_f32 v[24:25], v[62:63], v[4:5] op_sel_hi:[1,0]
	v_pk_mul_f32 v[22:23], v[40:41], v[22:23]
	v_pk_mul_f32 v[24:25], v[42:43], v[24:25]
	v_cvt_pk_bf16_f32 v22, v22, v23
	v_cvt_pk_bf16_f32 v23, v24, v25
	global_store_dwordx2 v[14:15], v[22:23], off offset:1072
	v_pk_mul_f32 v[22:23], v[96:97], v[4:5] op_sel_hi:[1,0]
	v_pk_mul_f32 v[24:25], v[92:93], v[4:5] op_sel_hi:[1,0]
	v_pk_mul_f32 v[4:5], v[12:13], v[4:5] op_sel_hi:[1,0]
	v_pk_mul_f32 v[22:23], v[44:45], v[22:23]
	v_pk_mul_f32 v[24:25], v[46:47], v[24:25]
	s_waitcnt vmcnt(0) lgkmcnt(0)
	v_pk_mul_f32 v[0:1], v[0:1], v[6:7]
	v_pk_mul_f32 v[2:3], v[2:3], v[4:5]
	v_cvt_pk_bf16_f32 v22, v22, v23
	v_cvt_pk_bf16_f32 v23, v24, v25
	v_cvt_pk_bf16_f32 v0, v0, v1
	v_cvt_pk_bf16_f32 v1, v2, v3
	global_store_dwordx2 v[14:15], v[22:23], off offset:1088
	global_store_dwordx2 v[14:15], v[0:1], off offset:1136
	s_cbranch_scc1 .LBB0_584
	s_cmpk_lt_i32 s14, 0x100
	s_cbranch_scc1 .LBB0_584
